# GEMM closing barrier one MFMA before the block end
# baseline (speedup 1.0000x reference)
;     __device__ __forceinline__ void stage_rs(const Unit& u, int tid, int wid) const { stage_rs_lds(SS, rsl, u, tid, wid); }
;     __device__ __forceinline__ void stage_rs(const Unit& u, int tid, int wid) const { stage_rs_lds(SS, rsl, u, tid, wid); }
; #define PG8_STAGE(bufoff, gbase, voff) do { _Pragma("unroll") for (int _i = 0; _i < 2; ++_i) \
;         __builtin_amdgcn_global_load_lds((const unsigned*)((const char*)(gbase) + (voff)[_i]), (PG8_LAS unsigned*)(lds + (bufoff) + ldsw + _i * 8192), 16, 0, 0); } while (0)
; #define PG8_LDA(dst, b, h) do { _Pragma("unroll") for (int m = 0; m < 4; ++m) _Pragma("unroll") for (int k = 0; k < 2; ++k) dst[m][k] = *(const PG8_LAS bf16x8*)(lds + PG8_SA(b, h) + aoff + m * 2048 + k * 1024); } while (0)
; #define PG8_LDB(dst, b, h) do { _Pragma("unroll") for (int n = 0; n < 2; ++n) _Pragma("unroll") for (int k = 0; k < 2; ++k) dst[n][k] = *(const PG8_LAS bf16x8*)(lds + PG8_SB(b, h) + boff + n * 2048 + k * 1024); } while (0)
; #define PG8_BAR __builtin_amdgcn_s_barrier()
; template <class Epi, class Sched, bool ALIGN_EPI = false, bool SP2 = false>
; __device__ __forceinline__ void gemm_phase(PG8_LAS unsigned char* lds, const Gemm g, const Sched& S, const Epi& E, const int tid) {
;     ...
;         for (int t = 0; t < nt; t += 2) {
;             const bool last = (t == nt - 2);
;             if constexpr (Epi::RS_LDS) { if (t == nt - 4) E.stage_rs(cur, tid, wid); }
;             if constexpr (Epi::PREFETCH) { if (t >= nt - 8) E.prefetch(cur, lds, tid, wid, (t - (nt - 8)) >> 1); }
;             const char* a1 = cA + (size_t)(t + 1) * kstep;
;             const char* a2 = last ? nA : cA + (size_t)(t + 2) * kstep; const char* b2 = last ? nB : cB + (size_t)(t + 2) * kstep;
;             const char* a3 = a2 + kstep; const char* b3 = b2 + kstep;
;             if (last && has_next) S.a_ready(nxt);
;             if constexpr (SP2) {
;             PG8_LDB(B0, 0, 0); PG8_LDB(B1, 0, 1); PG8_SCHED; PG8_LDA(At, 0, 0); PG8_STAGE(PG8_SA(1, 1), a1 + hstep, voffA);
;             PG8_WAIT_V(8); PG8_WAIT_L(0); PG8_BAR; PG8_MMA(0, 0, At, B0); PG8_MMA(0, 1, At, B1); PG8_BAR; PG8_SCHED;
;             PG8_LDA(At, 0, 1); PG8_STAGE(PG8_SB(0, 0), b2, voffB); PG8_STAGE(PG8_SB(0, 1), b2 + hstep, voffB); PG8_STAGE(PG8_SA(0, 0), a2, voffA);
;             PG8_WAIT_V(8); PG8_WAIT_L(0); PG8_BAR; PG8_MMA(1, 0, At, B0); PG8_MMA(1, 1, At, B1); PG8_BAR; PG8_SCHED;
.LBB0_87:
	s_add_u32 s38, s22, s68
	s_addc_u32 s39, s23, s69
	s_add_u32 s38, s38, 0x100
	s_addc_u32 s39, s39, 0
	s_add_u32 s50, s89, s68
	s_addc_u32 s51, s90, s69
	s_add_i32 s92, 0, 0x10000
	s_cmpk_eq_i32 s68, 0x700
	s_cselect_b32 s73, s15, s39
	s_cselect_b32 s72, s86, s38
	v_add_u32_e32 v150, s92, v153
	s_cselect_b32 s71, s87, s51
	s_cselect_b32 s70, s88, s50
	s_add_i32 s38, 0, 0x14000
	ds_read_b128 v[170:173], v150
	ds_read_b128 v[174:177], v150 offset:1024
	ds_read_b128 v[178:181], v150 offset:2048
	ds_read_b128 v[182:185], v150 offset:3072
	v_add_u32_e32 v150, s38, v153
	ds_read_b128 v[186:189], v150
	ds_read_b128 v[190:193], v150 offset:1024
	ds_read_b128 v[206:209], v150 offset:2048
	ds_read_b128 v[210:213], v150 offset:3072
	v_lshl_add_u64 v[246:247], v[146:147], 0, s[68:69]
	s_add_i32 m0, s76, 0xc000
	ds_read_b128 v[214:217], v167
	ds_read_b128 v[218:221], v167 offset:1024
	ds_read_b128 v[222:225], v167 offset:2048
	ds_read_b128 v[226:229], v167 offset:3072
	ds_read_b128 v[230:233], v167 offset:4096
	ds_read_b128 v[234:237], v167 offset:5120
	ds_read_b128 v[238:241], v167 offset:6144
	ds_read_b128 v[242:245], v167 offset:7168
	global_load_lds_dwordx4 v[246:247], off
	v_lshl_add_u64 v[246:247], v[148:149], 0, s[68:69]
	s_add_i32 m0, s76, 0xe000
	s_nop 0
	global_load_lds_dwordx4 v[246:247], off
	s_waitcnt vmcnt(8)
	s_waitcnt lgkmcnt(0)
	s_setprio 1
	s_barrier
	v_mfma_f32_16x16x32_bf16 v[126:129], v[170:173], v[214:217], v[126:129]
	v_mfma_f32_16x16x32_bf16 v[122:125], v[178:181], v[214:217], v[122:125]
	v_mfma_f32_16x16x32_bf16 v[110:113], v[170:173], v[222:225], v[110:113]
	v_mfma_f32_16x16x32_bf16 v[106:109], v[178:181], v[222:225], v[106:109]
	v_mfma_f32_16x16x32_bf16 v[94:97], v[170:173], v[230:233], v[94:97]
	v_mfma_f32_16x16x32_bf16 v[90:93], v[178:181], v[230:233], v[90:93]
	v_mfma_f32_16x16x32_bf16 v[78:81], v[170:173], v[238:241], v[78:81]
	v_mfma_f32_16x16x32_bf16 v[74:77], v[178:181], v[238:241], v[74:77]
	v_mfma_f32_16x16x32_bf16 v[126:129], v[174:177], v[218:221], v[126:129]
	v_mfma_f32_16x16x32_bf16 v[122:125], v[182:185], v[218:221], v[122:125]
	v_mfma_f32_16x16x32_bf16 v[110:113], v[174:177], v[226:229], v[110:113]
	v_mfma_f32_16x16x32_bf16 v[106:109], v[182:185], v[226:229], v[106:109]
	v_mfma_f32_16x16x32_bf16 v[94:97], v[174:177], v[234:237], v[94:97]
	v_mfma_f32_16x16x32_bf16 v[90:93], v[182:185], v[234:237], v[90:93]
	v_mfma_f32_16x16x32_bf16 v[78:81], v[174:177], v[242:245], v[78:81]
	v_mfma_f32_16x16x32_bf16 v[74:77], v[182:185], v[242:245], v[74:77]
	v_mfma_f32_16x16x32_bf16 v[118:121], v[186:189], v[214:217], v[118:121]
	v_mfma_f32_16x16x32_bf16 v[114:117], v[206:209], v[214:217], v[114:117]
	v_mfma_f32_16x16x32_bf16 v[102:105], v[186:189], v[222:225], v[102:105]
	v_mfma_f32_16x16x32_bf16 v[98:101], v[206:209], v[222:225], v[98:101]
	v_mfma_f32_16x16x32_bf16 v[86:89], v[186:189], v[230:233], v[86:89]
	v_mfma_f32_16x16x32_bf16 v[82:85], v[206:209], v[230:233], v[82:85]
	v_mfma_f32_16x16x32_bf16 v[70:73], v[186:189], v[238:241], v[70:73]
	v_mfma_f32_16x16x32_bf16 v[66:69], v[206:209], v[238:241], v[66:69]
	v_mfma_f32_16x16x32_bf16 v[118:121], v[190:193], v[218:221], v[118:121]
	v_mfma_f32_16x16x32_bf16 v[114:117], v[210:213], v[218:221], v[114:117]
	v_mfma_f32_16x16x32_bf16 v[102:105], v[190:193], v[226:229], v[102:105]
	v_mfma_f32_16x16x32_bf16 v[98:101], v[210:213], v[226:229], v[98:101]
	v_mfma_f32_16x16x32_bf16 v[86:89], v[190:193], v[234:237], v[86:89]
	v_mfma_f32_16x16x32_bf16 v[82:85], v[210:213], v[234:237], v[82:85]
	v_mfma_f32_16x16x32_bf16 v[70:73], v[190:193], v[242:245], v[70:73]
	s_barrier
	v_mfma_f32_16x16x32_bf16 v[66:69], v[210:213], v[242:245], v[66:69]
	s_setprio 0
	s_add_i32 s39, s92, s75
	v_lshl_add_u64 v[246:247], s[70:71], 0, v[0:1]
	s_mov_b32 m0, s39
	ds_read_b128 v[214:217], v167 offset:16384
	ds_read_b128 v[218:221], v167 offset:17408
	ds_read_b128 v[222:225], v167 offset:18432
	ds_read_b128 v[226:229], v167 offset:19456
	ds_read_b128 v[230:233], v167 offset:20480
	ds_read_b128 v[234:237], v167 offset:21504
	ds_read_b128 v[238:241], v167 offset:22528
	ds_read_b128 v[242:245], v167 offset:23552
	global_load_lds_dwordx4 v[246:247], off
	s_add_i32 m0, s39, 0x2000
	s_add_u32 s50, s70, 0x40000
	v_lshl_add_u64 v[248:249], s[70:71], 0, v[130:131]
	s_addc_u32 s51, s71, 0
	s_add_i32 s38, s38, s75
	global_load_lds_dwordx4 v[248:249], off
	v_lshl_add_u64 v[250:251], s[50:51], 0, v[0:1]
	s_mov_b32 m0, s38
	v_lshl_add_u64 v[252:253], s[72:73], 0, v[132:133]
	global_load_lds_dwordx4 v[250:251], off
	v_lshl_add_u64 v[250:251], s[50:51], 0, v[130:131]
	s_add_i32 m0, s38, 0x2000
	s_nop 0
	global_load_lds_dwordx4 v[250:251], off
	v_lshl_add_u64 v[250:251], s[72:73], 0, v[134:135]
	s_mov_b32 m0, s76
	s_nop 0
	global_load_lds_dwordx4 v[250:251], off
	s_mov_b32 m0, s77
	s_nop 0
	global_load_lds_dwordx4 v[252:253], off
	s_waitcnt vmcnt(8)
	s_waitcnt lgkmcnt(0)
	s_setprio 1
	s_barrier
; #define PG8_STAGE(bufoff, gbase, voff) do { _Pragma("unroll") for (int _i = 0; _i < 2; ++_i) \
;         __builtin_amdgcn_global_load_lds((const unsigned*)((const char*)(gbase) + (voff)[_i]), (PG8_LAS unsigned*)(lds + (bufoff) + ldsw + _i * 8192), 16, 0, 0); } while (0)
; #define PG8_LDA(dst, b, h) do { _Pragma("unroll") for (int m = 0; m < 4; ++m) _Pragma("unroll") for (int k = 0; k < 2; ++k) dst[m][k] = *(const PG8_LAS bf16x8*)(lds + PG8_SA(b, h) + aoff + m * 2048 + k * 1024); } while (0)
; #define PG8_LDB(dst, b, h) do { _Pragma("unroll") for (int n = 0; n < 2; ++n) _Pragma("unroll") for (int k = 0; k < 2; ++k) dst[n][k] = *(const PG8_LAS bf16x8*)(lds + PG8_SB(b, h) + boff + n * 2048 + k * 1024); } while (0)
; #define PG8_MMA(ai, bj, At, Bt) do { __builtin_amdgcn_s_setprio(1); _Pragma("unroll") for (int m = 0; m < 4; ++m) _Pragma("unroll") for (int n = 0; n < 2; ++n) _Pragma("unroll") for (int k = 0; k < 2; ++k) \
;         acc[ai][bj][m][n] = __builtin_amdgcn_mfma_f32_16x16x32_bf16(Bt[n][k], At[m][k], acc[ai][bj][m][n], 0, 0, 0); __builtin_amdgcn_s_setprio(0); } while (0)
; #define PG8_WAIT_V(n) asm volatile("s_waitcnt vmcnt(" #n ")" ::: "memory")
; #define PG8_WAIT_L(n) asm volatile("s_waitcnt lgkmcnt(" #n ")" ::: "memory")
; #define PG8_BAR __builtin_amdgcn_s_barrier()
; #define PG8_SCHED __builtin_amdgcn_sched_barrier(0)
; template <class Epi, class Sched, bool ALIGN_EPI = false, bool SP2 = false>
; __device__ __forceinline__ void gemm_phase(PG8_LAS unsigned char* lds, const Gemm g, const Sched& S, const Epi& E, const int tid) {
;     ...
;             PG8_WAIT_V(8); PG8_WAIT_L(0); PG8_BAR; PG8_MMA(1, 0, At, B0); PG8_MMA(1, 1, At, B1); PG8_BAR; PG8_SCHED;
;             PG8_LDB(B0, 1, 0); PG8_LDB(B1, 1, 1); PG8_SCHED; PG8_LDA(At, 1, 0); PG8_STAGE(PG8_SA(0, 1), a2 + hstep, voffA);
;             PG8_WAIT_V(8); PG8_WAIT_L(0); PG8_BAR; PG8_MMA(0, 0, At, B0); PG8_MMA(0, 1, At, B1); PG8_BAR; PG8_SCHED;
	v_mfma_f32_16x16x32_bf16 v[62:65], v[170:173], v[214:217], v[62:65]
	v_mfma_f32_16x16x32_bf16 v[58:61], v[178:181], v[214:217], v[58:61]
	v_mfma_f32_16x16x32_bf16 v[46:49], v[170:173], v[222:225], v[46:49]
	v_mfma_f32_16x16x32_bf16 v[42:45], v[178:181], v[222:225], v[42:45]
	v_mfma_f32_16x16x32_bf16 v[30:33], v[170:173], v[230:233], v[30:33]
	v_mfma_f32_16x16x32_bf16 v[26:29], v[178:181], v[230:233], v[26:29]
	v_mfma_f32_16x16x32_bf16 v[14:17], v[170:173], v[238:241], v[14:17]
	v_mfma_f32_16x16x32_bf16 v[10:13], v[178:181], v[238:241], v[10:13]
	v_mfma_f32_16x16x32_bf16 v[62:65], v[174:177], v[218:221], v[62:65]
	v_mfma_f32_16x16x32_bf16 v[58:61], v[182:185], v[218:221], v[58:61]
	v_mfma_f32_16x16x32_bf16 v[46:49], v[174:177], v[226:229], v[46:49]
	v_mfma_f32_16x16x32_bf16 v[42:45], v[182:185], v[226:229], v[42:45]
	v_mfma_f32_16x16x32_bf16 v[30:33], v[174:177], v[234:237], v[30:33]
	v_mfma_f32_16x16x32_bf16 v[26:29], v[182:185], v[234:237], v[26:29]
	v_mfma_f32_16x16x32_bf16 v[14:17], v[174:177], v[242:245], v[14:17]
	v_mfma_f32_16x16x32_bf16 v[10:13], v[182:185], v[242:245], v[10:13]
	v_mfma_f32_16x16x32_bf16 v[54:57], v[186:189], v[214:217], v[54:57]
	v_mfma_f32_16x16x32_bf16 v[50:53], v[206:209], v[214:217], v[50:53]
	v_mfma_f32_16x16x32_bf16 v[38:41], v[186:189], v[222:225], v[38:41]
	v_mfma_f32_16x16x32_bf16 v[34:37], v[206:209], v[222:225], v[34:37]
	v_mfma_f32_16x16x32_bf16 v[22:25], v[186:189], v[230:233], v[22:25]
	v_mfma_f32_16x16x32_bf16 v[18:21], v[206:209], v[230:233], v[18:21]
	v_mfma_f32_16x16x32_bf16 v[6:9], v[186:189], v[238:241], v[6:9]
	v_mfma_f32_16x16x32_bf16 v[2:5], v[206:209], v[238:241], v[2:5]
	v_mfma_f32_16x16x32_bf16 v[54:57], v[190:193], v[218:221], v[54:57]
	v_mfma_f32_16x16x32_bf16 v[50:53], v[210:213], v[218:221], v[50:53]
	v_mfma_f32_16x16x32_bf16 v[38:41], v[190:193], v[226:229], v[38:41]
	v_mfma_f32_16x16x32_bf16 v[34:37], v[210:213], v[226:229], v[34:37]
	v_mfma_f32_16x16x32_bf16 v[22:25], v[190:193], v[234:237], v[22:25]
	v_mfma_f32_16x16x32_bf16 v[18:21], v[210:213], v[234:237], v[18:21]
	v_mfma_f32_16x16x32_bf16 v[6:9], v[190:193], v[242:245], v[6:9]
	s_barrier
	v_mfma_f32_16x16x32_bf16 v[2:5], v[210:213], v[242:245], v[2:5]
	s_setprio 0
	s_add_i32 s38, 0, 0x18000
	v_add_u32_e32 v150, s38, v153
	s_add_i32 s39, 0, 0x1c000
	ds_read_b128 v[170:173], v150
	ds_read_b128 v[174:177], v150 offset:1024
	ds_read_b128 v[178:181], v150 offset:2048
	ds_read_b128 v[182:185], v150 offset:3072
	v_add_u32_e32 v150, s39, v153
	ds_read_b128 v[186:189], v150
	ds_read_b128 v[190:193], v150 offset:1024
	ds_read_b128 v[206:209], v150 offset:2048
	ds_read_b128 v[210:213], v150 offset:3072
	s_add_u32 s50, s72, 0x40000
	s_addc_u32 s51, s73, 0
	s_mov_b32 m0, s78
	v_lshl_add_u64 v[194:195], s[50:51], 0, v[134:135]
	ds_read_b128 v[214:217], v167 offset:32768
	ds_read_b128 v[218:221], v167 offset:33792
	ds_read_b128 v[222:225], v167 offset:34816
	ds_read_b128 v[226:229], v167 offset:35840
	ds_read_b128 v[230:233], v167 offset:36864
	ds_read_b128 v[234:237], v167 offset:37888
	ds_read_b128 v[238:241], v167 offset:38912
	ds_read_b128 v[242:245], v167 offset:39936
	global_load_lds_dwordx4 v[194:195], off
	v_lshl_add_u64 v[194:195], s[50:51], 0, v[132:133]
	s_mov_b32 m0, s79
	s_nop 0
	global_load_lds_dwordx4 v[194:195], off
	s_waitcnt vmcnt(8)
	s_waitcnt lgkmcnt(0)
	s_setprio 1
	s_barrier
	v_mfma_f32_16x16x32_bf16 v[126:129], v[170:173], v[214:217], v[126:129]
	v_mfma_f32_16x16x32_bf16 v[122:125], v[178:181], v[214:217], v[122:125]
	v_mfma_f32_16x16x32_bf16 v[110:113], v[170:173], v[222:225], v[110:113]
	v_mfma_f32_16x16x32_bf16 v[106:109], v[178:181], v[222:225], v[106:109]
	v_mfma_f32_16x16x32_bf16 v[94:97], v[170:173], v[230:233], v[94:97]
	v_mfma_f32_16x16x32_bf16 v[90:93], v[178:181], v[230:233], v[90:93]
	v_mfma_f32_16x16x32_bf16 v[78:81], v[170:173], v[238:241], v[78:81]
	v_mfma_f32_16x16x32_bf16 v[74:77], v[178:181], v[238:241], v[74:77]
	v_mfma_f32_16x16x32_bf16 v[126:129], v[174:177], v[218:221], v[126:129]
	v_mfma_f32_16x16x32_bf16 v[122:125], v[182:185], v[218:221], v[122:125]
	v_mfma_f32_16x16x32_bf16 v[110:113], v[174:177], v[226:229], v[110:113]
	v_mfma_f32_16x16x32_bf16 v[106:109], v[182:185], v[226:229], v[106:109]
	v_mfma_f32_16x16x32_bf16 v[94:97], v[174:177], v[234:237], v[94:97]
	v_mfma_f32_16x16x32_bf16 v[90:93], v[182:185], v[234:237], v[90:93]
	v_mfma_f32_16x16x32_bf16 v[78:81], v[174:177], v[242:245], v[78:81]
	v_mfma_f32_16x16x32_bf16 v[74:77], v[182:185], v[242:245], v[74:77]
	v_mfma_f32_16x16x32_bf16 v[118:121], v[186:189], v[214:217], v[118:121]
	v_mfma_f32_16x16x32_bf16 v[114:117], v[206:209], v[214:217], v[114:117]
	v_mfma_f32_16x16x32_bf16 v[102:105], v[186:189], v[222:225], v[102:105]
	v_mfma_f32_16x16x32_bf16 v[98:101], v[206:209], v[222:225], v[98:101]
	v_mfma_f32_16x16x32_bf16 v[86:89], v[186:189], v[230:233], v[86:89]
	v_mfma_f32_16x16x32_bf16 v[82:85], v[206:209], v[230:233], v[82:85]
	v_mfma_f32_16x16x32_bf16 v[70:73], v[186:189], v[238:241], v[70:73]
	v_mfma_f32_16x16x32_bf16 v[66:69], v[206:209], v[238:241], v[66:69]
	v_mfma_f32_16x16x32_bf16 v[118:121], v[190:193], v[218:221], v[118:121]
	v_mfma_f32_16x16x32_bf16 v[114:117], v[210:213], v[218:221], v[114:117]
	v_mfma_f32_16x16x32_bf16 v[102:105], v[190:193], v[226:229], v[102:105]
	v_mfma_f32_16x16x32_bf16 v[98:101], v[210:213], v[226:229], v[98:101]
	v_mfma_f32_16x16x32_bf16 v[86:89], v[190:193], v[234:237], v[86:89]
	v_mfma_f32_16x16x32_bf16 v[82:85], v[210:213], v[234:237], v[82:85]
	v_mfma_f32_16x16x32_bf16 v[70:73], v[190:193], v[242:245], v[70:73]
	s_barrier
; #define PG8_STAGE(bufoff, gbase, voff) do { _Pragma("unroll") for (int _i = 0; _i < 2; ++_i) \
;         __builtin_amdgcn_global_load_lds((const unsigned*)((const char*)(gbase) + (voff)[_i]), (PG8_LAS unsigned*)(lds + (bufoff) + ldsw + _i * 8192), 16, 0, 0); } while (0)
; #define PG8_LDA(dst, b, h) do { _Pragma("unroll") for (int m = 0; m < 4; ++m) _Pragma("unroll") for (int k = 0; k < 2; ++k) dst[m][k] = *(const PG8_LAS bf16x8*)(lds + PG8_SA(b, h) + aoff + m * 2048 + k * 1024); } while (0)
; #define PG8_MMA(ai, bj, At, Bt) do { __builtin_amdgcn_s_setprio(1); _Pragma("unroll") for (int m = 0; m < 4; ++m) _Pragma("unroll") for (int n = 0; n < 2; ++n) _Pragma("unroll") for (int k = 0; k < 2; ++k) \
;         acc[ai][bj][m][n] = __builtin_amdgcn_mfma_f32_16x16x32_bf16(Bt[n][k], At[m][k], acc[ai][bj][m][n], 0, 0, 0); __builtin_amdgcn_s_setprio(0); } while (0)
; #define PG8_WAIT_V(n) asm volatile("s_waitcnt vmcnt(" #n ")" ::: "memory")
; #define PG8_WAIT_L(n) asm volatile("s_waitcnt lgkmcnt(" #n ")" ::: "memory")
; #define PG8_BAR __builtin_amdgcn_s_barrier()
; #define PG8_SCHED __builtin_amdgcn_sched_barrier(0)
; template <class Epi, class Sched, bool ALIGN_EPI = false, bool SP2 = false>
; __device__ __forceinline__ void gemm_phase(PG8_LAS unsigned char* lds, const Gemm g, const Sched& S, const Epi& E, const int tid) {
;     ...
;             PG8_LDA(At, 1, 1); PG8_STAGE(PG8_SB(1, 0), b3, voffB); PG8_STAGE(PG8_SB(1, 1), b3 + hstep, voffB); PG8_STAGE(PG8_SA(1, 0), a3, voffA);
;             PG8_WAIT_V(8); PG8_WAIT_L(0); PG8_BAR; PG8_MMA(1, 0, At, B0); PG8_MMA(1, 1, At, B1); PG8_BAR; PG8_SCHED;
	v_mfma_f32_16x16x32_bf16 v[66:69], v[210:213], v[242:245], v[66:69]
	s_setprio 0
	s_add_i32 s38, s38, s75
	v_lshl_add_u64 v[194:195], v[246:247], 0, s[56:57]
	s_mov_b32 m0, s38
	ds_read_b128 v[214:217], v167 offset:49152
	ds_read_b128 v[218:221], v167 offset:50176
	ds_read_b128 v[222:225], v167 offset:51200
	ds_read_b128 v[226:229], v167 offset:52224
	ds_read_b128 v[230:233], v167 offset:53248
	ds_read_b128 v[234:237], v167 offset:54272
	ds_read_b128 v[238:241], v167 offset:55296
	ds_read_b128 v[242:245], v167 offset:56320
	global_load_lds_dwordx4 v[194:195], off
	s_add_i32 m0, s38, 0x2000
	s_add_u32 s50, s70, 0x40080
	v_lshl_add_u64 v[194:195], v[248:249], 0, s[56:57]
	s_addc_u32 s51, s71, 0
	s_add_i32 s38, s39, s75
	global_load_lds_dwordx4 v[194:195], off
	v_lshl_add_u64 v[194:195], s[50:51], 0, v[0:1]
	s_mov_b32 m0, s38
	s_nop 0
	global_load_lds_dwordx4 v[194:195], off
	v_lshl_add_u64 v[194:195], s[50:51], 0, v[130:131]
	s_add_i32 m0, s38, 0x2000
	s_nop 0
	global_load_lds_dwordx4 v[194:195], off
	v_lshl_add_u64 v[194:195], v[250:251], 0, s[56:57]
	s_mov_b32 m0, s80
	s_nop 0
	global_load_lds_dwordx4 v[194:195], off
	v_lshl_add_u64 v[194:195], v[252:253], 0, s[56:57]
	s_mov_b32 m0, s81
	s_nop 0
	global_load_lds_dwordx4 v[194:195], off
	s_waitcnt vmcnt(8)
	s_waitcnt lgkmcnt(0)
	s_setprio 1
	s_barrier
	v_mfma_f32_16x16x32_bf16 v[62:65], v[170:173], v[214:217], v[62:65]
	v_mfma_f32_16x16x32_bf16 v[58:61], v[178:181], v[214:217], v[58:61]
	v_mfma_f32_16x16x32_bf16 v[46:49], v[170:173], v[222:225], v[46:49]
	v_mfma_f32_16x16x32_bf16 v[42:45], v[178:181], v[222:225], v[42:45]
	v_mfma_f32_16x16x32_bf16 v[30:33], v[170:173], v[230:233], v[30:33]
	v_mfma_f32_16x16x32_bf16 v[26:29], v[178:181], v[230:233], v[26:29]
	v_mfma_f32_16x16x32_bf16 v[14:17], v[170:173], v[238:241], v[14:17]
	v_mfma_f32_16x16x32_bf16 v[10:13], v[178:181], v[238:241], v[10:13]
	v_mfma_f32_16x16x32_bf16 v[62:65], v[174:177], v[218:221], v[62:65]
	v_mfma_f32_16x16x32_bf16 v[58:61], v[182:185], v[218:221], v[58:61]
	v_mfma_f32_16x16x32_bf16 v[46:49], v[174:177], v[226:229], v[46:49]
	v_mfma_f32_16x16x32_bf16 v[42:45], v[182:185], v[226:229], v[42:45]
	v_mfma_f32_16x16x32_bf16 v[30:33], v[174:177], v[234:237], v[30:33]
	v_mfma_f32_16x16x32_bf16 v[26:29], v[182:185], v[234:237], v[26:29]
	v_mfma_f32_16x16x32_bf16 v[14:17], v[174:177], v[242:245], v[14:17]
	v_mfma_f32_16x16x32_bf16 v[10:13], v[182:185], v[242:245], v[10:13]
	v_mfma_f32_16x16x32_bf16 v[54:57], v[186:189], v[214:217], v[54:57]
	v_mfma_f32_16x16x32_bf16 v[50:53], v[206:209], v[214:217], v[50:53]
	v_mfma_f32_16x16x32_bf16 v[38:41], v[186:189], v[222:225], v[38:41]
	v_mfma_f32_16x16x32_bf16 v[34:37], v[206:209], v[222:225], v[34:37]
	v_mfma_f32_16x16x32_bf16 v[22:25], v[186:189], v[230:233], v[22:25]
	v_mfma_f32_16x16x32_bf16 v[18:21], v[206:209], v[230:233], v[18:21]
	v_mfma_f32_16x16x32_bf16 v[6:9], v[186:189], v[238:241], v[6:9]
	v_mfma_f32_16x16x32_bf16 v[2:5], v[206:209], v[238:241], v[2:5]
	v_mfma_f32_16x16x32_bf16 v[54:57], v[190:193], v[218:221], v[54:57]
	v_mfma_f32_16x16x32_bf16 v[50:53], v[210:213], v[218:221], v[50:53]
	v_mfma_f32_16x16x32_bf16 v[38:41], v[190:193], v[226:229], v[38:41]
	v_mfma_f32_16x16x32_bf16 v[34:37], v[210:213], v[226:229], v[34:37]
	v_mfma_f32_16x16x32_bf16 v[22:25], v[190:193], v[234:237], v[22:25]
	v_mfma_f32_16x16x32_bf16 v[18:21], v[210:213], v[234:237], v[18:21]
	v_mfma_f32_16x16x32_bf16 v[6:9], v[190:193], v[242:245], v[6:9]
	s_barrier
	v_mfma_f32_16x16x32_bf16 v[2:5], v[210:213], v[242:245], v[2:5]
	s_setprio 0
	s_add_i32 s91, s91, 2
	s_add_u32 s68, s68, 0x100
	s_addc_u32 s69, s69, 0
	s_cmp_gt_u32 s91, 13
	s_cbranch_scc1 .LBB0_90

;     __device__ __forceinline__ void stage_rs(const Unit& u, int tid, int wid) const { stage_rs_lds(SS, rsl, u, tid, wid); }
;     __device__ __forceinline__ void stage_rs(const Unit& u, int tid, int wid) const { stage_rs_lds(SS, rsl, u, tid, wid); }
; #define PG8_STAGE(bufoff, gbase, voff) do { _Pragma("unroll") for (int _i = 0; _i < 2; ++_i) \
;         __builtin_amdgcn_global_load_lds((const unsigned*)((const char*)(gbase) + (voff)[_i]), (PG8_LAS unsigned*)(lds + (bufoff) + ldsw + _i * 8192), 16, 0, 0); } while (0)
; #define PG8_LDA(dst, b, h) do { _Pragma("unroll") for (int m = 0; m < 4; ++m) _Pragma("unroll") for (int k = 0; k < 2; ++k) dst[m][k] = *(const PG8_LAS bf16x8*)(lds + PG8_SA(b, h) + aoff + m * 2048 + k * 1024); } while (0)
; #define PG8_LDB(dst, b, h) do { _Pragma("unroll") for (int n = 0; n < 2; ++n) _Pragma("unroll") for (int k = 0; k < 2; ++k) dst[n][k] = *(const PG8_LAS bf16x8*)(lds + PG8_SB(b, h) + boff + n * 2048 + k * 1024); } while (0)
; #define PG8_BAR __builtin_amdgcn_s_barrier()
; template <class Epi, class Sched, bool ALIGN_EPI = false, bool SP2 = false>
; __device__ __forceinline__ void gemm_phase(PG8_LAS unsigned char* lds, const Gemm g, const Sched& S, const Epi& E, const int tid) {
;     ...
;         for (int t = 0; t < nt; t += 2) {
;             const bool last = (t == nt - 2);
;             if constexpr (Epi::RS_LDS) { if (t == nt - 4) E.stage_rs(cur, tid, wid); }
;             if constexpr (Epi::PREFETCH) { if (t >= nt - 8) E.prefetch(cur, lds, tid, wid, (t - (nt - 8)) >> 1); }
;             const char* a1 = cA + (size_t)(t + 1) * kstep;
;             const char* a2 = last ? nA : cA + (size_t)(t + 2) * kstep; const char* b2 = last ? nB : cB + (size_t)(t + 2) * kstep;
;             const char* a3 = a2 + kstep; const char* b3 = b2 + kstep;
;             if (last && has_next) S.a_ready(nxt);
;             if constexpr (SP2) {
;             PG8_LDB(B0, 0, 0); PG8_LDB(B1, 0, 1); PG8_SCHED; PG8_LDA(At, 0, 0); PG8_STAGE(PG8_SA(1, 1), a1 + hstep, voffA);
;             PG8_WAIT_V(8); PG8_WAIT_L(0); PG8_BAR; PG8_MMA(0, 0, At, B0); PG8_MMA(0, 1, At, B1); PG8_BAR; PG8_SCHED;
;             PG8_LDA(At, 0, 1); PG8_STAGE(PG8_SB(0, 0), b2, voffB); PG8_STAGE(PG8_SB(0, 1), b2 + hstep, voffB); PG8_STAGE(PG8_SA(0, 0), a2, voffA);
;             PG8_WAIT_V(8); PG8_WAIT_L(0); PG8_BAR; PG8_MMA(1, 0, At, B0); PG8_MMA(1, 1, At, B1); PG8_BAR; PG8_SCHED;
.LBB0_208:
	s_add_u32 s38, s10, s12
	s_addc_u32 s39, s11, s13
	s_add_u32 s38, s38, 0x100
	s_addc_u32 s39, s39, 0
	s_add_u32 s51, vcc_lo, s12
	s_addc_u32 s74, vcc_hi, s13
	s_add_i32 s59, 0, 0x10000
	s_cmpk_eq_i32 s12, 0x700
	s_cselect_b32 s77, s49, s39
	s_cselect_b32 s76, s78, s38
	v_add_u32_e32 v0, s59, v153
	s_cselect_b32 s75, s69, s74
	s_cselect_b32 s74, s79, s51
	s_add_i32 s51, 0, 0x14000
	ds_read_b128 v[170:173], v0
	ds_read_b128 v[174:177], v0 offset:1024
	ds_read_b128 v[178:181], v0 offset:2048
	ds_read_b128 v[182:185], v0 offset:3072
	v_add_u32_e32 v0, s51, v153
	ds_read_b128 v[186:189], v0
	ds_read_b128 v[190:193], v0 offset:1024
	ds_read_b128 v[206:209], v0 offset:2048
	ds_read_b128 v[210:213], v0 offset:3072
	v_lshl_add_u64 v[194:195], v[148:149], 0, s[12:13]
	s_add_i32 m0, s84, 0xc000
	ds_read_b128 v[214:217], v167
	ds_read_b128 v[218:221], v167 offset:1024
	ds_read_b128 v[222:225], v167 offset:2048
	ds_read_b128 v[226:229], v167 offset:3072
	ds_read_b128 v[230:233], v167 offset:4096
	ds_read_b128 v[234:237], v167 offset:5120
	ds_read_b128 v[238:241], v167 offset:6144
	ds_read_b128 v[242:245], v167 offset:7168
	global_load_lds_dwordx4 v[194:195], off
	v_lshl_add_u64 v[194:195], v[150:151], 0, s[12:13]
	s_add_i32 m0, s84, 0xe000
	s_nop 0
	global_load_lds_dwordx4 v[194:195], off
	s_waitcnt vmcnt(8)
	s_waitcnt lgkmcnt(0)
	s_setprio 1
	s_barrier
	v_mfma_f32_16x16x32_bf16 v[126:129], v[170:173], v[214:217], v[126:129]
	v_mfma_f32_16x16x32_bf16 v[122:125], v[178:181], v[214:217], v[122:125]
	v_mfma_f32_16x16x32_bf16 v[110:113], v[170:173], v[222:225], v[110:113]
	v_mfma_f32_16x16x32_bf16 v[106:109], v[178:181], v[222:225], v[106:109]
	v_mfma_f32_16x16x32_bf16 v[94:97], v[170:173], v[230:233], v[94:97]
	v_mfma_f32_16x16x32_bf16 v[90:93], v[178:181], v[230:233], v[90:93]
	v_mfma_f32_16x16x32_bf16 v[78:81], v[170:173], v[238:241], v[78:81]
	v_mfma_f32_16x16x32_bf16 v[74:77], v[178:181], v[238:241], v[74:77]
	v_mfma_f32_16x16x32_bf16 v[126:129], v[174:177], v[218:221], v[126:129]
	v_mfma_f32_16x16x32_bf16 v[122:125], v[182:185], v[218:221], v[122:125]
	v_mfma_f32_16x16x32_bf16 v[110:113], v[174:177], v[226:229], v[110:113]
	v_mfma_f32_16x16x32_bf16 v[106:109], v[182:185], v[226:229], v[106:109]
	v_mfma_f32_16x16x32_bf16 v[94:97], v[174:177], v[234:237], v[94:97]
	v_mfma_f32_16x16x32_bf16 v[90:93], v[182:185], v[234:237], v[90:93]
	v_mfma_f32_16x16x32_bf16 v[78:81], v[174:177], v[242:245], v[78:81]
	v_mfma_f32_16x16x32_bf16 v[74:77], v[182:185], v[242:245], v[74:77]
	v_mfma_f32_16x16x32_bf16 v[118:121], v[186:189], v[214:217], v[118:121]
	v_mfma_f32_16x16x32_bf16 v[114:117], v[206:209], v[214:217], v[114:117]
	v_mfma_f32_16x16x32_bf16 v[102:105], v[186:189], v[222:225], v[102:105]
	v_mfma_f32_16x16x32_bf16 v[98:101], v[206:209], v[222:225], v[98:101]
	v_mfma_f32_16x16x32_bf16 v[86:89], v[186:189], v[230:233], v[86:89]
	v_mfma_f32_16x16x32_bf16 v[82:85], v[206:209], v[230:233], v[82:85]
	v_mfma_f32_16x16x32_bf16 v[70:73], v[186:189], v[238:241], v[70:73]
	v_mfma_f32_16x16x32_bf16 v[66:69], v[206:209], v[238:241], v[66:69]
	v_mfma_f32_16x16x32_bf16 v[118:121], v[190:193], v[218:221], v[118:121]
	v_mfma_f32_16x16x32_bf16 v[114:117], v[210:213], v[218:221], v[114:117]
	v_mfma_f32_16x16x32_bf16 v[102:105], v[190:193], v[226:229], v[102:105]
	v_mfma_f32_16x16x32_bf16 v[98:101], v[210:213], v[226:229], v[98:101]
	v_mfma_f32_16x16x32_bf16 v[86:89], v[190:193], v[234:237], v[86:89]
	v_mfma_f32_16x16x32_bf16 v[82:85], v[210:213], v[234:237], v[82:85]
	v_mfma_f32_16x16x32_bf16 v[70:73], v[190:193], v[242:245], v[70:73]
	s_barrier
	v_mfma_f32_16x16x32_bf16 v[66:69], v[210:213], v[242:245], v[66:69]
	s_setprio 0
	s_add_i32 s38, s59, s83
	v_lshl_add_u64 v[194:195], s[74:75], 0, v[134:135]
	s_mov_b32 m0, s38
	ds_read_b128 v[214:217], v167 offset:16384
	ds_read_b128 v[218:221], v167 offset:17408
	ds_read_b128 v[222:225], v167 offset:18432
	ds_read_b128 v[226:229], v167 offset:19456
	ds_read_b128 v[230:233], v167 offset:20480
	ds_read_b128 v[234:237], v167 offset:21504
	ds_read_b128 v[238:241], v167 offset:22528
	ds_read_b128 v[242:245], v167 offset:23552
	global_load_lds_dwordx4 v[194:195], off
	s_add_i32 m0, s38, 0x2000
	s_add_u32 s38, s74, 0x40000
	v_lshl_add_u64 v[246:247], s[74:75], 0, v[130:131]
	s_addc_u32 s39, s75, 0
	s_add_i32 s51, s51, s83
	global_load_lds_dwordx4 v[246:247], off
	v_lshl_add_u64 v[248:249], s[38:39], 0, v[134:135]
	s_mov_b32 m0, s51
	v_lshl_add_u64 v[250:251], s[76:77], 0, v[132:133]
	global_load_lds_dwordx4 v[248:249], off
	v_lshl_add_u64 v[248:249], s[38:39], 0, v[130:131]
	s_add_i32 m0, s51, 0x2000
	s_nop 0
	global_load_lds_dwordx4 v[248:249], off
	v_lshl_add_u64 v[248:249], s[76:77], 0, v[136:137]
	s_mov_b32 m0, s84
	s_nop 0
	global_load_lds_dwordx4 v[248:249], off
	s_mov_b32 m0, s85
	s_nop 0
	global_load_lds_dwordx4 v[250:251], off
	s_waitcnt vmcnt(8)
	s_waitcnt lgkmcnt(0)
	s_setprio 1
	s_barrier
; #define PG8_STAGE(bufoff, gbase, voff) do { _Pragma("unroll") for (int _i = 0; _i < 2; ++_i) \
;         __builtin_amdgcn_global_load_lds((const unsigned*)((const char*)(gbase) + (voff)[_i]), (PG8_LAS unsigned*)(lds + (bufoff) + ldsw + _i * 8192), 16, 0, 0); } while (0)
; #define PG8_LDA(dst, b, h) do { _Pragma("unroll") for (int m = 0; m < 4; ++m) _Pragma("unroll") for (int k = 0; k < 2; ++k) dst[m][k] = *(const PG8_LAS bf16x8*)(lds + PG8_SA(b, h) + aoff + m * 2048 + k * 1024); } while (0)
; #define PG8_LDB(dst, b, h) do { _Pragma("unroll") for (int n = 0; n < 2; ++n) _Pragma("unroll") for (int k = 0; k < 2; ++k) dst[n][k] = *(const PG8_LAS bf16x8*)(lds + PG8_SB(b, h) + boff + n * 2048 + k * 1024); } while (0)
; #define PG8_MMA(ai, bj, At, Bt) do { __builtin_amdgcn_s_setprio(1); _Pragma("unroll") for (int m = 0; m < 4; ++m) _Pragma("unroll") for (int n = 0; n < 2; ++n) _Pragma("unroll") for (int k = 0; k < 2; ++k) \
;         acc[ai][bj][m][n] = __builtin_amdgcn_mfma_f32_16x16x32_bf16(Bt[n][k], At[m][k], acc[ai][bj][m][n], 0, 0, 0); __builtin_amdgcn_s_setprio(0); } while (0)
; #define PG8_WAIT_V(n) asm volatile("s_waitcnt vmcnt(" #n ")" ::: "memory")
; #define PG8_WAIT_L(n) asm volatile("s_waitcnt lgkmcnt(" #n ")" ::: "memory")
; #define PG8_BAR __builtin_amdgcn_s_barrier()
; #define PG8_SCHED __builtin_amdgcn_sched_barrier(0)
; template <class Epi, class Sched, bool ALIGN_EPI = false, bool SP2 = false>
; __device__ __forceinline__ void gemm_phase(PG8_LAS unsigned char* lds, const Gemm g, const Sched& S, const Epi& E, const int tid) {
;     ...
;             PG8_WAIT_V(8); PG8_WAIT_L(0); PG8_BAR; PG8_MMA(1, 0, At, B0); PG8_MMA(1, 1, At, B1); PG8_BAR; PG8_SCHED;
;             PG8_LDB(B0, 1, 0); PG8_LDB(B1, 1, 1); PG8_SCHED; PG8_LDA(At, 1, 0); PG8_STAGE(PG8_SA(0, 1), a2 + hstep, voffA);
;             PG8_WAIT_V(8); PG8_WAIT_L(0); PG8_BAR; PG8_MMA(0, 0, At, B0); PG8_MMA(0, 1, At, B1); PG8_BAR; PG8_SCHED;
	v_mfma_f32_16x16x32_bf16 v[62:65], v[170:173], v[214:217], v[62:65]
	v_mfma_f32_16x16x32_bf16 v[58:61], v[178:181], v[214:217], v[58:61]
	v_mfma_f32_16x16x32_bf16 v[46:49], v[170:173], v[222:225], v[46:49]
	v_mfma_f32_16x16x32_bf16 v[42:45], v[178:181], v[222:225], v[42:45]
	v_mfma_f32_16x16x32_bf16 v[30:33], v[170:173], v[230:233], v[30:33]
	v_mfma_f32_16x16x32_bf16 v[26:29], v[178:181], v[230:233], v[26:29]
	v_mfma_f32_16x16x32_bf16 v[14:17], v[170:173], v[238:241], v[14:17]
	v_mfma_f32_16x16x32_bf16 v[10:13], v[178:181], v[238:241], v[10:13]
	v_mfma_f32_16x16x32_bf16 v[62:65], v[174:177], v[218:221], v[62:65]
	v_mfma_f32_16x16x32_bf16 v[58:61], v[182:185], v[218:221], v[58:61]
	v_mfma_f32_16x16x32_bf16 v[46:49], v[174:177], v[226:229], v[46:49]
	v_mfma_f32_16x16x32_bf16 v[42:45], v[182:185], v[226:229], v[42:45]
	v_mfma_f32_16x16x32_bf16 v[30:33], v[174:177], v[234:237], v[30:33]
	v_mfma_f32_16x16x32_bf16 v[26:29], v[182:185], v[234:237], v[26:29]
	v_mfma_f32_16x16x32_bf16 v[14:17], v[174:177], v[242:245], v[14:17]
	v_mfma_f32_16x16x32_bf16 v[10:13], v[182:185], v[242:245], v[10:13]
	v_mfma_f32_16x16x32_bf16 v[54:57], v[186:189], v[214:217], v[54:57]
	v_mfma_f32_16x16x32_bf16 v[50:53], v[206:209], v[214:217], v[50:53]
	v_mfma_f32_16x16x32_bf16 v[38:41], v[186:189], v[222:225], v[38:41]
	v_mfma_f32_16x16x32_bf16 v[34:37], v[206:209], v[222:225], v[34:37]
	v_mfma_f32_16x16x32_bf16 v[22:25], v[186:189], v[230:233], v[22:25]
	v_mfma_f32_16x16x32_bf16 v[18:21], v[206:209], v[230:233], v[18:21]
	v_mfma_f32_16x16x32_bf16 v[6:9], v[186:189], v[238:241], v[6:9]
	v_mfma_f32_16x16x32_bf16 v[2:5], v[206:209], v[238:241], v[2:5]
	v_mfma_f32_16x16x32_bf16 v[54:57], v[190:193], v[218:221], v[54:57]
	v_mfma_f32_16x16x32_bf16 v[50:53], v[210:213], v[218:221], v[50:53]
	v_mfma_f32_16x16x32_bf16 v[38:41], v[190:193], v[226:229], v[38:41]
	v_mfma_f32_16x16x32_bf16 v[34:37], v[210:213], v[226:229], v[34:37]
	v_mfma_f32_16x16x32_bf16 v[22:25], v[190:193], v[234:237], v[22:25]
	v_mfma_f32_16x16x32_bf16 v[18:21], v[210:213], v[234:237], v[18:21]
	v_mfma_f32_16x16x32_bf16 v[6:9], v[190:193], v[242:245], v[6:9]
	s_barrier
	v_mfma_f32_16x16x32_bf16 v[2:5], v[210:213], v[242:245], v[2:5]
	s_setprio 0
	s_add_i32 s51, 0, 0x18000
	v_add_u32_e32 v0, s51, v153
	s_add_i32 s59, 0, 0x1c000
	ds_read_b128 v[170:173], v0
	ds_read_b128 v[174:177], v0 offset:1024
	ds_read_b128 v[178:181], v0 offset:2048
	ds_read_b128 v[182:185], v0 offset:3072
	v_add_u32_e32 v0, s59, v153
	ds_read_b128 v[186:189], v0
	ds_read_b128 v[190:193], v0 offset:1024
	ds_read_b128 v[206:209], v0 offset:2048
	ds_read_b128 v[210:213], v0 offset:3072
	s_add_u32 s38, s76, 0x40000
	s_addc_u32 s39, s77, 0
	s_mov_b32 m0, s86
	v_lshl_add_u64 v[252:253], s[38:39], 0, v[136:137]
	ds_read_b128 v[214:217], v167 offset:32768
	ds_read_b128 v[218:221], v167 offset:33792
	ds_read_b128 v[222:225], v167 offset:34816
	ds_read_b128 v[226:229], v167 offset:35840
	ds_read_b128 v[230:233], v167 offset:36864
	ds_read_b128 v[234:237], v167 offset:37888
	ds_read_b128 v[238:241], v167 offset:38912
	ds_read_b128 v[242:245], v167 offset:39936
	global_load_lds_dwordx4 v[252:253], off
	v_lshl_add_u64 v[252:253], s[38:39], 0, v[132:133]
	s_mov_b32 m0, s87
	s_nop 0
	global_load_lds_dwordx4 v[252:253], off
	s_waitcnt vmcnt(8)
	s_waitcnt lgkmcnt(0)
	s_setprio 1
	s_barrier
	v_mfma_f32_16x16x32_bf16 v[126:129], v[170:173], v[214:217], v[126:129]
	v_mfma_f32_16x16x32_bf16 v[122:125], v[178:181], v[214:217], v[122:125]
	v_mfma_f32_16x16x32_bf16 v[110:113], v[170:173], v[222:225], v[110:113]
	v_mfma_f32_16x16x32_bf16 v[106:109], v[178:181], v[222:225], v[106:109]
	v_mfma_f32_16x16x32_bf16 v[94:97], v[170:173], v[230:233], v[94:97]
	v_mfma_f32_16x16x32_bf16 v[90:93], v[178:181], v[230:233], v[90:93]
	v_mfma_f32_16x16x32_bf16 v[78:81], v[170:173], v[238:241], v[78:81]
	v_mfma_f32_16x16x32_bf16 v[74:77], v[178:181], v[238:241], v[74:77]
	v_mfma_f32_16x16x32_bf16 v[126:129], v[174:177], v[218:221], v[126:129]
	v_mfma_f32_16x16x32_bf16 v[122:125], v[182:185], v[218:221], v[122:125]
	v_mfma_f32_16x16x32_bf16 v[110:113], v[174:177], v[226:229], v[110:113]
	v_mfma_f32_16x16x32_bf16 v[106:109], v[182:185], v[226:229], v[106:109]
	v_mfma_f32_16x16x32_bf16 v[94:97], v[174:177], v[234:237], v[94:97]
	v_mfma_f32_16x16x32_bf16 v[90:93], v[182:185], v[234:237], v[90:93]
	v_mfma_f32_16x16x32_bf16 v[78:81], v[174:177], v[242:245], v[78:81]
	v_mfma_f32_16x16x32_bf16 v[74:77], v[182:185], v[242:245], v[74:77]
	v_mfma_f32_16x16x32_bf16 v[118:121], v[186:189], v[214:217], v[118:121]
	v_mfma_f32_16x16x32_bf16 v[114:117], v[206:209], v[214:217], v[114:117]
	v_mfma_f32_16x16x32_bf16 v[102:105], v[186:189], v[222:225], v[102:105]
	v_mfma_f32_16x16x32_bf16 v[98:101], v[206:209], v[222:225], v[98:101]
	v_mfma_f32_16x16x32_bf16 v[86:89], v[186:189], v[230:233], v[86:89]
	v_mfma_f32_16x16x32_bf16 v[82:85], v[206:209], v[230:233], v[82:85]
	v_mfma_f32_16x16x32_bf16 v[70:73], v[186:189], v[238:241], v[70:73]
	v_mfma_f32_16x16x32_bf16 v[66:69], v[206:209], v[238:241], v[66:69]
	v_mfma_f32_16x16x32_bf16 v[118:121], v[190:193], v[218:221], v[118:121]
	v_mfma_f32_16x16x32_bf16 v[114:117], v[210:213], v[218:221], v[114:117]
	v_mfma_f32_16x16x32_bf16 v[102:105], v[190:193], v[226:229], v[102:105]
	v_mfma_f32_16x16x32_bf16 v[98:101], v[210:213], v[226:229], v[98:101]
	v_mfma_f32_16x16x32_bf16 v[86:89], v[190:193], v[234:237], v[86:89]
	v_mfma_f32_16x16x32_bf16 v[82:85], v[210:213], v[234:237], v[82:85]
	v_mfma_f32_16x16x32_bf16 v[70:73], v[190:193], v[242:245], v[70:73]
	s_barrier
; #define PG8_STAGE(bufoff, gbase, voff) do { _Pragma("unroll") for (int _i = 0; _i < 2; ++_i) \
;         __builtin_amdgcn_global_load_lds((const unsigned*)((const char*)(gbase) + (voff)[_i]), (PG8_LAS unsigned*)(lds + (bufoff) + ldsw + _i * 8192), 16, 0, 0); } while (0)
; #define PG8_LDA(dst, b, h) do { _Pragma("unroll") for (int m = 0; m < 4; ++m) _Pragma("unroll") for (int k = 0; k < 2; ++k) dst[m][k] = *(const PG8_LAS bf16x8*)(lds + PG8_SA(b, h) + aoff + m * 2048 + k * 1024); } while (0)
; #define PG8_MMA(ai, bj, At, Bt) do { __builtin_amdgcn_s_setprio(1); _Pragma("unroll") for (int m = 0; m < 4; ++m) _Pragma("unroll") for (int n = 0; n < 2; ++n) _Pragma("unroll") for (int k = 0; k < 2; ++k) \
;         acc[ai][bj][m][n] = __builtin_amdgcn_mfma_f32_16x16x32_bf16(Bt[n][k], At[m][k], acc[ai][bj][m][n], 0, 0, 0); __builtin_amdgcn_s_setprio(0); } while (0)
; #define PG8_WAIT_V(n) asm volatile("s_waitcnt vmcnt(" #n ")" ::: "memory")
; #define PG8_WAIT_L(n) asm volatile("s_waitcnt lgkmcnt(" #n ")" ::: "memory")
; #define PG8_BAR __builtin_amdgcn_s_barrier()
; #define PG8_SCHED __builtin_amdgcn_sched_barrier(0)
; template <class Epi, class Sched, bool ALIGN_EPI = false, bool SP2 = false>
; __device__ __forceinline__ void gemm_phase(PG8_LAS unsigned char* lds, const Gemm g, const Sched& S, const Epi& E, const int tid) {
;     ...
;             PG8_LDA(At, 1, 1); PG8_STAGE(PG8_SB(1, 0), b3, voffB); PG8_STAGE(PG8_SB(1, 1), b3 + hstep, voffB); PG8_STAGE(PG8_SA(1, 0), a3, voffA);
;             PG8_WAIT_V(8); PG8_WAIT_L(0); PG8_BAR; PG8_MMA(1, 0, At, B0); PG8_MMA(1, 1, At, B1); PG8_BAR; PG8_SCHED;
	v_mfma_f32_16x16x32_bf16 v[66:69], v[210:213], v[242:245], v[66:69]
	s_setprio 0
	s_add_i32 s38, s51, s83
	v_lshl_add_u64 v[194:195], v[194:195], 0, s[56:57]
	s_mov_b32 m0, s38
	ds_read_b128 v[214:217], v167 offset:49152
	ds_read_b128 v[218:221], v167 offset:50176
	ds_read_b128 v[222:225], v167 offset:51200
	ds_read_b128 v[226:229], v167 offset:52224
	ds_read_b128 v[230:233], v167 offset:53248
	ds_read_b128 v[234:237], v167 offset:54272
	ds_read_b128 v[238:241], v167 offset:55296
	ds_read_b128 v[242:245], v167 offset:56320
	global_load_lds_dwordx4 v[194:195], off
	s_add_i32 m0, s38, 0x2000
	s_add_u32 s38, s74, 0x40080
	v_lshl_add_u64 v[194:195], v[246:247], 0, s[56:57]
	s_addc_u32 s39, s75, 0
	s_add_i32 s51, s59, s83
	global_load_lds_dwordx4 v[194:195], off
	v_lshl_add_u64 v[194:195], s[38:39], 0, v[134:135]
	s_mov_b32 m0, s51
	s_nop 0
	global_load_lds_dwordx4 v[194:195], off
	v_lshl_add_u64 v[194:195], s[38:39], 0, v[130:131]
	s_add_i32 m0, s51, 0x2000
	s_nop 0
	global_load_lds_dwordx4 v[194:195], off
	v_lshl_add_u64 v[194:195], v[248:249], 0, s[56:57]
	s_mov_b32 m0, s88
	s_nop 0
	global_load_lds_dwordx4 v[194:195], off
	v_lshl_add_u64 v[194:195], v[250:251], 0, s[56:57]
	s_mov_b32 m0, s89
	s_nop 0
	global_load_lds_dwordx4 v[194:195], off
	s_waitcnt vmcnt(8)
	s_waitcnt lgkmcnt(0)
	s_setprio 1
	s_barrier
	v_mfma_f32_16x16x32_bf16 v[62:65], v[170:173], v[214:217], v[62:65]
	v_mfma_f32_16x16x32_bf16 v[58:61], v[178:181], v[214:217], v[58:61]
	v_mfma_f32_16x16x32_bf16 v[46:49], v[170:173], v[222:225], v[46:49]
	v_mfma_f32_16x16x32_bf16 v[42:45], v[178:181], v[222:225], v[42:45]
	v_mfma_f32_16x16x32_bf16 v[30:33], v[170:173], v[230:233], v[30:33]
	v_mfma_f32_16x16x32_bf16 v[26:29], v[178:181], v[230:233], v[26:29]
	v_mfma_f32_16x16x32_bf16 v[14:17], v[170:173], v[238:241], v[14:17]
	v_mfma_f32_16x16x32_bf16 v[10:13], v[178:181], v[238:241], v[10:13]
	v_mfma_f32_16x16x32_bf16 v[62:65], v[174:177], v[218:221], v[62:65]
	v_mfma_f32_16x16x32_bf16 v[58:61], v[182:185], v[218:221], v[58:61]
	v_mfma_f32_16x16x32_bf16 v[46:49], v[174:177], v[226:229], v[46:49]
	v_mfma_f32_16x16x32_bf16 v[42:45], v[182:185], v[226:229], v[42:45]
	v_mfma_f32_16x16x32_bf16 v[30:33], v[174:177], v[234:237], v[30:33]
	v_mfma_f32_16x16x32_bf16 v[26:29], v[182:185], v[234:237], v[26:29]
	v_mfma_f32_16x16x32_bf16 v[14:17], v[174:177], v[242:245], v[14:17]
	v_mfma_f32_16x16x32_bf16 v[10:13], v[182:185], v[242:245], v[10:13]
	v_mfma_f32_16x16x32_bf16 v[54:57], v[186:189], v[214:217], v[54:57]
	v_mfma_f32_16x16x32_bf16 v[50:53], v[206:209], v[214:217], v[50:53]
	v_mfma_f32_16x16x32_bf16 v[38:41], v[186:189], v[222:225], v[38:41]
	v_mfma_f32_16x16x32_bf16 v[34:37], v[206:209], v[222:225], v[34:37]
	v_mfma_f32_16x16x32_bf16 v[22:25], v[186:189], v[230:233], v[22:25]
	v_mfma_f32_16x16x32_bf16 v[18:21], v[206:209], v[230:233], v[18:21]
	v_mfma_f32_16x16x32_bf16 v[6:9], v[186:189], v[238:241], v[6:9]
	v_mfma_f32_16x16x32_bf16 v[2:5], v[206:209], v[238:241], v[2:5]
	v_mfma_f32_16x16x32_bf16 v[54:57], v[190:193], v[218:221], v[54:57]
	v_mfma_f32_16x16x32_bf16 v[50:53], v[210:213], v[218:221], v[50:53]
	v_mfma_f32_16x16x32_bf16 v[38:41], v[190:193], v[226:229], v[38:41]
	v_mfma_f32_16x16x32_bf16 v[34:37], v[210:213], v[226:229], v[34:37]
	v_mfma_f32_16x16x32_bf16 v[22:25], v[190:193], v[234:237], v[22:25]
	v_mfma_f32_16x16x32_bf16 v[18:21], v[210:213], v[234:237], v[18:21]
	v_mfma_f32_16x16x32_bf16 v[6:9], v[190:193], v[242:245], v[6:9]
	s_barrier
	v_mfma_f32_16x16x32_bf16 v[2:5], v[210:213], v[242:245], v[2:5]
	s_setprio 0
	s_add_i32 s50, s50, 2
	s_add_u32 s12, s12, 0x100
	s_addc_u32 s13, s13, 0
	s_cmp_gt_u32 s50, 13
	s_cbranch_scc1 .LBB0_211

;     __device__ __forceinline__ void stage_rs(const Unit& u, int tid, int wid) const { stage_rs_lds(SS, rsl, u, tid, wid); }
;     __device__ __forceinline__ void stage_rs(const Unit& u, int tid, int wid) const { stage_rs_lds(SS, rsl, u, tid, wid); }
; #define PG8_STAGE(bufoff, gbase, voff) do { _Pragma("unroll") for (int _i = 0; _i < 2; ++_i) \
;         __builtin_amdgcn_global_load_lds((const unsigned*)((const char*)(gbase) + (voff)[_i]), (PG8_LAS unsigned*)(lds + (bufoff) + ldsw + _i * 8192), 16, 0, 0); } while (0)
; #define PG8_LDA(dst, b, h) do { _Pragma("unroll") for (int m = 0; m < 4; ++m) _Pragma("unroll") for (int k = 0; k < 2; ++k) dst[m][k] = *(const PG8_LAS bf16x8*)(lds + PG8_SA(b, h) + aoff + m * 2048 + k * 1024); } while (0)
; #define PG8_LDB(dst, b, h) do { _Pragma("unroll") for (int n = 0; n < 2; ++n) _Pragma("unroll") for (int k = 0; k < 2; ++k) dst[n][k] = *(const PG8_LAS bf16x8*)(lds + PG8_SB(b, h) + boff + n * 2048 + k * 1024); } while (0)
; #define PG8_BAR __builtin_amdgcn_s_barrier()
; template <class Epi, class Sched, bool ALIGN_EPI = false, bool SP2 = false>
; __device__ __forceinline__ void gemm_phase(PG8_LAS unsigned char* lds, const Gemm g, const Sched& S, const Epi& E, const int tid) {
;     ...
;         for (int t = 0; t < nt; t += 2) {
;             const bool last = (t == nt - 2);
;             if constexpr (Epi::RS_LDS) { if (t == nt - 4) E.stage_rs(cur, tid, wid); }
;             if constexpr (Epi::PREFETCH) { if (t >= nt - 8) E.prefetch(cur, lds, tid, wid, (t - (nt - 8)) >> 1); }
;             const char* a1 = cA + (size_t)(t + 1) * kstep;
;             const char* a2 = last ? nA : cA + (size_t)(t + 2) * kstep; const char* b2 = last ? nB : cB + (size_t)(t + 2) * kstep;
;             const char* a3 = a2 + kstep; const char* b3 = b2 + kstep;
;             if (last && has_next) S.a_ready(nxt);
;             if constexpr (SP2) {
;             PG8_LDB(B0, 0, 0); PG8_LDB(B1, 0, 1); PG8_SCHED; PG8_LDA(At, 0, 0); PG8_STAGE(PG8_SA(1, 1), a1 + hstep, voffA);
;             PG8_WAIT_V(8); PG8_WAIT_L(0); PG8_BAR; PG8_MMA(0, 0, At, B0); PG8_MMA(0, 1, At, B1); PG8_BAR; PG8_SCHED;
;             PG8_LDA(At, 0, 1); PG8_STAGE(PG8_SB(0, 0), b2, voffB); PG8_STAGE(PG8_SB(0, 1), b2 + hstep, voffB); PG8_STAGE(PG8_SA(0, 0), a2, voffA);
;             PG8_WAIT_V(8); PG8_WAIT_L(0); PG8_BAR; PG8_MMA(1, 0, At, B0); PG8_MMA(1, 1, At, B1); PG8_BAR; PG8_SCHED;
.LBB0_618:
	s_add_i32 s85, s70, 2
	s_add_u32 s38, s68, 0x80
	s_addc_u32 s39, s69, 0
	s_add_i32 s59, 0, 0x10000
	s_cmp_eq_u32 s81, s70
	s_cselect_b32 s71, s11, s39
	s_cselect_b32 s70, s10, s38
	s_cselect_b32 s39, s67, s51
	s_cselect_b32 s38, s66, s50
	s_add_i32 s86, 0, 0x14000
	v_add_u32_e32 v142, s59, v205
	v_add_u32_e32 v180, s86, v205
	ds_read_b128 v[130:133], v142
	ds_read_b128 v[134:137], v142 offset:1024
	ds_read_b128 v[138:141], v142 offset:2048
	ds_read_b128 v[142:145], v142 offset:3072
	ds_read_b128 v[146:149], v180
	ds_read_b128 v[150:153], v180 offset:1024
	ds_read_b128 v[176:179], v180 offset:2048
	ds_read_b128 v[180:183], v180 offset:3072
	v_lshl_add_u64 v[192:193], s[68:69], 0, v[172:173]
	s_add_i32 m0, s73, 0xc000
	ds_read_b128 v[184:187], v207
	ds_read_b128 v[188:191], v207 offset:1024
	ds_read_b128 v[208:211], v207 offset:2048
	ds_read_b128 v[212:215], v207 offset:3072
	ds_read_b128 v[216:219], v207 offset:4096
	ds_read_b128 v[220:223], v207 offset:5120
	ds_read_b128 v[224:227], v207 offset:6144
	ds_read_b128 v[228:231], v207 offset:7168
	global_load_lds_dwordx4 v[192:193], off
	v_lshl_add_u64 v[192:193], s[68:69], 0, v[174:175]
	s_add_i32 m0, s73, 0xe000
	s_nop 0
	global_load_lds_dwordx4 v[192:193], off
	s_waitcnt vmcnt(8)
	s_waitcnt lgkmcnt(0)
	s_setprio 1
	s_barrier
	v_mfma_f32_16x16x32_bf16 v[126:129], v[130:133], v[184:187], v[126:129]
	v_mfma_f32_16x16x32_bf16 v[122:125], v[138:141], v[184:187], v[122:125]
	v_mfma_f32_16x16x32_bf16 v[110:113], v[130:133], v[208:211], v[110:113]
	v_mfma_f32_16x16x32_bf16 v[106:109], v[138:141], v[208:211], v[106:109]
	v_mfma_f32_16x16x32_bf16 v[94:97], v[130:133], v[216:219], v[94:97]
	v_mfma_f32_16x16x32_bf16 v[90:93], v[138:141], v[216:219], v[90:93]
	v_mfma_f32_16x16x32_bf16 v[78:81], v[130:133], v[224:227], v[78:81]
	v_mfma_f32_16x16x32_bf16 v[74:77], v[138:141], v[224:227], v[74:77]
	v_mfma_f32_16x16x32_bf16 v[126:129], v[134:137], v[188:191], v[126:129]
	v_mfma_f32_16x16x32_bf16 v[122:125], v[142:145], v[188:191], v[122:125]
	v_mfma_f32_16x16x32_bf16 v[110:113], v[134:137], v[212:215], v[110:113]
	v_mfma_f32_16x16x32_bf16 v[106:109], v[142:145], v[212:215], v[106:109]
	v_mfma_f32_16x16x32_bf16 v[94:97], v[134:137], v[220:223], v[94:97]
	v_mfma_f32_16x16x32_bf16 v[90:93], v[142:145], v[220:223], v[90:93]
	v_mfma_f32_16x16x32_bf16 v[78:81], v[134:137], v[228:231], v[78:81]
	v_mfma_f32_16x16x32_bf16 v[74:77], v[142:145], v[228:231], v[74:77]
	v_mfma_f32_16x16x32_bf16 v[118:121], v[146:149], v[184:187], v[118:121]
	v_mfma_f32_16x16x32_bf16 v[114:117], v[176:179], v[184:187], v[114:117]
	v_mfma_f32_16x16x32_bf16 v[102:105], v[146:149], v[208:211], v[102:105]
	v_mfma_f32_16x16x32_bf16 v[98:101], v[176:179], v[208:211], v[98:101]
	v_mfma_f32_16x16x32_bf16 v[86:89], v[146:149], v[216:219], v[86:89]
	v_mfma_f32_16x16x32_bf16 v[82:85], v[176:179], v[216:219], v[82:85]
	v_mfma_f32_16x16x32_bf16 v[70:73], v[146:149], v[224:227], v[70:73]
	v_mfma_f32_16x16x32_bf16 v[66:69], v[176:179], v[224:227], v[66:69]
	v_mfma_f32_16x16x32_bf16 v[118:121], v[150:153], v[188:191], v[118:121]
	v_mfma_f32_16x16x32_bf16 v[114:117], v[180:183], v[188:191], v[114:117]
	v_mfma_f32_16x16x32_bf16 v[102:105], v[150:153], v[212:215], v[102:105]
	v_mfma_f32_16x16x32_bf16 v[98:101], v[180:183], v[212:215], v[98:101]
	v_mfma_f32_16x16x32_bf16 v[86:89], v[150:153], v[220:223], v[86:89]
	v_mfma_f32_16x16x32_bf16 v[82:85], v[180:183], v[220:223], v[82:85]
	v_mfma_f32_16x16x32_bf16 v[70:73], v[150:153], v[228:231], v[70:73]
	s_barrier
	v_mfma_f32_16x16x32_bf16 v[66:69], v[180:183], v[228:231], v[66:69]
	s_setprio 0
	s_add_i32 s59, s59, s72
	v_lshl_add_u64 v[192:193], s[38:39], 0, v[0:1]
	s_mov_b32 m0, s59
	ds_read_b128 v[184:187], v207 offset:16384
	ds_read_b128 v[188:191], v207 offset:17408
	ds_read_b128 v[208:211], v207 offset:18432
	ds_read_b128 v[212:215], v207 offset:19456
	ds_read_b128 v[216:219], v207 offset:20480
	ds_read_b128 v[220:223], v207 offset:21504
	ds_read_b128 v[224:227], v207 offset:22528
	ds_read_b128 v[228:231], v207 offset:23552
	global_load_lds_dwordx4 v[192:193], off
	s_add_i32 m0, s59, 0x2000
	v_lshl_add_u64 v[194:195], s[38:39], 0, v[166:167]
	s_add_u32 s38, s38, s14
	s_addc_u32 s39, s39, 0
	s_add_i32 s59, s86, s72
	global_load_lds_dwordx4 v[194:195], off
	v_lshl_add_u64 v[232:233], s[38:39], 0, v[0:1]
	s_mov_b32 m0, s59
	v_lshl_add_u64 v[234:235], s[38:39], 0, v[166:167]
	global_load_lds_dwordx4 v[232:233], off
	s_add_i32 m0, s59, 0x2000
	v_lshl_add_u64 v[236:237], s[70:71], 0, v[170:171]
	global_load_lds_dwordx4 v[234:235], off
	s_mov_b32 m0, s73
	v_lshl_add_u64 v[238:239], s[70:71], 0, v[168:169]
	global_load_lds_dwordx4 v[236:237], off
	s_mov_b32 m0, s74
	s_nop 0
	global_load_lds_dwordx4 v[238:239], off
	s_waitcnt vmcnt(8)
	s_waitcnt lgkmcnt(0)
	s_setprio 1
	s_barrier
; #define PG8_STAGE(bufoff, gbase, voff) do { _Pragma("unroll") for (int _i = 0; _i < 2; ++_i) \
;         __builtin_amdgcn_global_load_lds((const unsigned*)((const char*)(gbase) + (voff)[_i]), (PG8_LAS unsigned*)(lds + (bufoff) + ldsw + _i * 8192), 16, 0, 0); } while (0)
; #define PG8_LDA(dst, b, h) do { _Pragma("unroll") for (int m = 0; m < 4; ++m) _Pragma("unroll") for (int k = 0; k < 2; ++k) dst[m][k] = *(const PG8_LAS bf16x8*)(lds + PG8_SA(b, h) + aoff + m * 2048 + k * 1024); } while (0)
; #define PG8_LDB(dst, b, h) do { _Pragma("unroll") for (int n = 0; n < 2; ++n) _Pragma("unroll") for (int k = 0; k < 2; ++k) dst[n][k] = *(const PG8_LAS bf16x8*)(lds + PG8_SB(b, h) + boff + n * 2048 + k * 1024); } while (0)
; #define PG8_MMA(ai, bj, At, Bt) do { __builtin_amdgcn_s_setprio(1); _Pragma("unroll") for (int m = 0; m < 4; ++m) _Pragma("unroll") for (int n = 0; n < 2; ++n) _Pragma("unroll") for (int k = 0; k < 2; ++k) \
;         acc[ai][bj][m][n] = __builtin_amdgcn_mfma_f32_16x16x32_bf16(Bt[n][k], At[m][k], acc[ai][bj][m][n], 0, 0, 0); __builtin_amdgcn_s_setprio(0); } while (0)
; #define PG8_WAIT_V(n) asm volatile("s_waitcnt vmcnt(" #n ")" ::: "memory")
; #define PG8_WAIT_L(n) asm volatile("s_waitcnt lgkmcnt(" #n ")" ::: "memory")
; #define PG8_BAR __builtin_amdgcn_s_barrier()
; #define PG8_SCHED __builtin_amdgcn_sched_barrier(0)
; template <class Epi, class Sched, bool ALIGN_EPI = false, bool SP2 = false>
; __device__ __forceinline__ void gemm_phase(PG8_LAS unsigned char* lds, const Gemm g, const Sched& S, const Epi& E, const int tid) {
;     ...
;             PG8_WAIT_V(8); PG8_WAIT_L(0); PG8_BAR; PG8_MMA(1, 0, At, B0); PG8_MMA(1, 1, At, B1); PG8_BAR; PG8_SCHED;
;             PG8_LDB(B0, 1, 0); PG8_LDB(B1, 1, 1); PG8_SCHED; PG8_LDA(At, 1, 0); PG8_STAGE(PG8_SA(0, 1), a2 + hstep, voffA);
;             PG8_WAIT_V(8); PG8_WAIT_L(0); PG8_BAR; PG8_MMA(0, 0, At, B0); PG8_MMA(0, 1, At, B1); PG8_BAR; PG8_SCHED;
	v_mfma_f32_16x16x32_bf16 v[62:65], v[130:133], v[184:187], v[62:65]
	v_mfma_f32_16x16x32_bf16 v[58:61], v[138:141], v[184:187], v[58:61]
	v_mfma_f32_16x16x32_bf16 v[46:49], v[130:133], v[208:211], v[46:49]
	v_mfma_f32_16x16x32_bf16 v[42:45], v[138:141], v[208:211], v[42:45]
	v_mfma_f32_16x16x32_bf16 v[30:33], v[130:133], v[216:219], v[30:33]
	v_mfma_f32_16x16x32_bf16 v[26:29], v[138:141], v[216:219], v[26:29]
	v_mfma_f32_16x16x32_bf16 v[14:17], v[130:133], v[224:227], v[14:17]
	v_mfma_f32_16x16x32_bf16 v[10:13], v[138:141], v[224:227], v[10:13]
	v_mfma_f32_16x16x32_bf16 v[62:65], v[134:137], v[188:191], v[62:65]
	v_mfma_f32_16x16x32_bf16 v[58:61], v[142:145], v[188:191], v[58:61]
	v_mfma_f32_16x16x32_bf16 v[46:49], v[134:137], v[212:215], v[46:49]
	v_mfma_f32_16x16x32_bf16 v[42:45], v[142:145], v[212:215], v[42:45]
	v_mfma_f32_16x16x32_bf16 v[30:33], v[134:137], v[220:223], v[30:33]
	v_mfma_f32_16x16x32_bf16 v[26:29], v[142:145], v[220:223], v[26:29]
	v_mfma_f32_16x16x32_bf16 v[14:17], v[134:137], v[228:231], v[14:17]
	v_mfma_f32_16x16x32_bf16 v[10:13], v[142:145], v[228:231], v[10:13]
	v_mfma_f32_16x16x32_bf16 v[54:57], v[146:149], v[184:187], v[54:57]
	v_mfma_f32_16x16x32_bf16 v[50:53], v[176:179], v[184:187], v[50:53]
	v_mfma_f32_16x16x32_bf16 v[38:41], v[146:149], v[208:211], v[38:41]
	v_mfma_f32_16x16x32_bf16 v[34:37], v[176:179], v[208:211], v[34:37]
	v_mfma_f32_16x16x32_bf16 v[22:25], v[146:149], v[216:219], v[22:25]
	v_mfma_f32_16x16x32_bf16 v[18:21], v[176:179], v[216:219], v[18:21]
	v_mfma_f32_16x16x32_bf16 v[6:9], v[146:149], v[224:227], v[6:9]
	v_mfma_f32_16x16x32_bf16 v[2:5], v[176:179], v[224:227], v[2:5]
	v_mfma_f32_16x16x32_bf16 v[54:57], v[150:153], v[188:191], v[54:57]
	v_mfma_f32_16x16x32_bf16 v[50:53], v[180:183], v[188:191], v[50:53]
	v_mfma_f32_16x16x32_bf16 v[38:41], v[150:153], v[212:215], v[38:41]
	v_mfma_f32_16x16x32_bf16 v[34:37], v[180:183], v[212:215], v[34:37]
	v_mfma_f32_16x16x32_bf16 v[22:25], v[150:153], v[220:223], v[22:25]
	v_mfma_f32_16x16x32_bf16 v[18:21], v[180:183], v[220:223], v[18:21]
	v_mfma_f32_16x16x32_bf16 v[6:9], v[150:153], v[228:231], v[6:9]
	s_barrier
	v_mfma_f32_16x16x32_bf16 v[2:5], v[180:183], v[228:231], v[2:5]
	s_setprio 0
	s_add_i32 s59, 0, 0x18000
	s_add_i32 s86, 0, 0x1c000
	v_add_u32_e32 v142, s59, v205
	v_add_u32_e32 v180, s86, v205
	ds_read_b128 v[130:133], v142
	ds_read_b128 v[134:137], v142 offset:1024
	ds_read_b128 v[138:141], v142 offset:2048
	ds_read_b128 v[142:145], v142 offset:3072
	ds_read_b128 v[146:149], v180
	ds_read_b128 v[150:153], v180 offset:1024
	ds_read_b128 v[176:179], v180 offset:2048
	ds_read_b128 v[180:183], v180 offset:3072
	s_add_u32 s38, s70, s14
	s_addc_u32 s39, s71, 0
	s_mov_b32 m0, s75
	v_lshl_add_u64 v[240:241], s[38:39], 0, v[170:171]
	ds_read_b128 v[184:187], v207 offset:32768
	ds_read_b128 v[188:191], v207 offset:33792
	ds_read_b128 v[208:211], v207 offset:34816
	ds_read_b128 v[212:215], v207 offset:35840
	ds_read_b128 v[216:219], v207 offset:36864
	ds_read_b128 v[220:223], v207 offset:37888
	ds_read_b128 v[224:227], v207 offset:38912
	ds_read_b128 v[228:231], v207 offset:39936
	global_load_lds_dwordx4 v[240:241], off
	v_lshl_add_u64 v[240:241], s[38:39], 0, v[168:169]
	s_mov_b32 m0, s76
	s_nop 0
	global_load_lds_dwordx4 v[240:241], off
	s_waitcnt vmcnt(8)
	s_waitcnt lgkmcnt(0)
	s_setprio 1
	s_barrier
	v_mfma_f32_16x16x32_bf16 v[126:129], v[130:133], v[184:187], v[126:129]
	v_mfma_f32_16x16x32_bf16 v[122:125], v[138:141], v[184:187], v[122:125]
	v_mfma_f32_16x16x32_bf16 v[110:113], v[130:133], v[208:211], v[110:113]
	v_mfma_f32_16x16x32_bf16 v[106:109], v[138:141], v[208:211], v[106:109]
	v_mfma_f32_16x16x32_bf16 v[94:97], v[130:133], v[216:219], v[94:97]
	v_mfma_f32_16x16x32_bf16 v[90:93], v[138:141], v[216:219], v[90:93]
	v_mfma_f32_16x16x32_bf16 v[78:81], v[130:133], v[224:227], v[78:81]
	v_mfma_f32_16x16x32_bf16 v[74:77], v[138:141], v[224:227], v[74:77]
	v_mfma_f32_16x16x32_bf16 v[126:129], v[134:137], v[188:191], v[126:129]
	v_mfma_f32_16x16x32_bf16 v[122:125], v[142:145], v[188:191], v[122:125]
	v_mfma_f32_16x16x32_bf16 v[110:113], v[134:137], v[212:215], v[110:113]
	v_mfma_f32_16x16x32_bf16 v[106:109], v[142:145], v[212:215], v[106:109]
	v_mfma_f32_16x16x32_bf16 v[94:97], v[134:137], v[220:223], v[94:97]
	v_mfma_f32_16x16x32_bf16 v[90:93], v[142:145], v[220:223], v[90:93]
	v_mfma_f32_16x16x32_bf16 v[78:81], v[134:137], v[228:231], v[78:81]
	v_mfma_f32_16x16x32_bf16 v[74:77], v[142:145], v[228:231], v[74:77]
	v_mfma_f32_16x16x32_bf16 v[118:121], v[146:149], v[184:187], v[118:121]
	v_mfma_f32_16x16x32_bf16 v[114:117], v[176:179], v[184:187], v[114:117]
	v_mfma_f32_16x16x32_bf16 v[102:105], v[146:149], v[208:211], v[102:105]
	v_mfma_f32_16x16x32_bf16 v[98:101], v[176:179], v[208:211], v[98:101]
	v_mfma_f32_16x16x32_bf16 v[86:89], v[146:149], v[216:219], v[86:89]
	v_mfma_f32_16x16x32_bf16 v[82:85], v[176:179], v[216:219], v[82:85]
	v_mfma_f32_16x16x32_bf16 v[70:73], v[146:149], v[224:227], v[70:73]
	v_mfma_f32_16x16x32_bf16 v[66:69], v[176:179], v[224:227], v[66:69]
	v_mfma_f32_16x16x32_bf16 v[118:121], v[150:153], v[188:191], v[118:121]
	v_mfma_f32_16x16x32_bf16 v[114:117], v[180:183], v[188:191], v[114:117]
	v_mfma_f32_16x16x32_bf16 v[102:105], v[150:153], v[212:215], v[102:105]
	v_mfma_f32_16x16x32_bf16 v[98:101], v[180:183], v[212:215], v[98:101]
	v_mfma_f32_16x16x32_bf16 v[86:89], v[150:153], v[220:223], v[86:89]
	v_mfma_f32_16x16x32_bf16 v[82:85], v[180:183], v[220:223], v[82:85]
	v_mfma_f32_16x16x32_bf16 v[70:73], v[150:153], v[228:231], v[70:73]
	s_barrier
; #define PG8_STAGE(bufoff, gbase, voff) do { _Pragma("unroll") for (int _i = 0; _i < 2; ++_i) \
;         __builtin_amdgcn_global_load_lds((const unsigned*)((const char*)(gbase) + (voff)[_i]), (PG8_LAS unsigned*)(lds + (bufoff) + ldsw + _i * 8192), 16, 0, 0); } while (0)
; #define PG8_LDA(dst, b, h) do { _Pragma("unroll") for (int m = 0; m < 4; ++m) _Pragma("unroll") for (int k = 0; k < 2; ++k) dst[m][k] = *(const PG8_LAS bf16x8*)(lds + PG8_SA(b, h) + aoff + m * 2048 + k * 1024); } while (0)
; #define PG8_MMA(ai, bj, At, Bt) do { __builtin_amdgcn_s_setprio(1); _Pragma("unroll") for (int m = 0; m < 4; ++m) _Pragma("unroll") for (int n = 0; n < 2; ++n) _Pragma("unroll") for (int k = 0; k < 2; ++k) \
;         acc[ai][bj][m][n] = __builtin_amdgcn_mfma_f32_16x16x32_bf16(Bt[n][k], At[m][k], acc[ai][bj][m][n], 0, 0, 0); __builtin_amdgcn_s_setprio(0); } while (0)
; #define PG8_WAIT_V(n) asm volatile("s_waitcnt vmcnt(" #n ")" ::: "memory")
; #define PG8_WAIT_L(n) asm volatile("s_waitcnt lgkmcnt(" #n ")" ::: "memory")
; #define PG8_BAR __builtin_amdgcn_s_barrier()
; #define PG8_SCHED __builtin_amdgcn_sched_barrier(0)
; template <class Epi, class Sched, bool ALIGN_EPI = false, bool SP2 = false>
; __device__ __forceinline__ void gemm_phase(PG8_LAS unsigned char* lds, const Gemm g, const Sched& S, const Epi& E, const int tid) {
;     ...
;             PG8_LDA(At, 1, 1); PG8_STAGE(PG8_SB(1, 0), b3, voffB); PG8_STAGE(PG8_SB(1, 1), b3 + hstep, voffB); PG8_STAGE(PG8_SA(1, 0), a3, voffA);
;             PG8_WAIT_V(8); PG8_WAIT_L(0); PG8_BAR; PG8_MMA(1, 0, At, B0); PG8_MMA(1, 1, At, B1); PG8_BAR; PG8_SCHED;
;     ...
;         if constexpr (ALIGN_EPI) { if (wr == 0) PG8_BAR; }
	v_mfma_f32_16x16x32_bf16 v[66:69], v[180:183], v[228:231], v[66:69]
	s_setprio 0
	s_add_i32 s38, s59, s72
	v_lshl_add_u64 v[192:193], v[192:193], 0, s[56:57]
	s_mov_b32 m0, s38
	ds_read_b128 v[184:187], v207 offset:49152
	ds_read_b128 v[188:191], v207 offset:50176
	ds_read_b128 v[208:211], v207 offset:51200
	ds_read_b128 v[212:215], v207 offset:52224
	ds_read_b128 v[216:219], v207 offset:53248
	ds_read_b128 v[220:223], v207 offset:54272
	ds_read_b128 v[224:227], v207 offset:55296
	ds_read_b128 v[228:231], v207 offset:56320
	global_load_lds_dwordx4 v[192:193], off
	v_lshl_add_u64 v[192:193], v[194:195], 0, s[56:57]
	s_add_i32 m0, s38, 0x2000
	s_add_i32 s38, s86, s72
	global_load_lds_dwordx4 v[192:193], off
	v_lshl_add_u64 v[192:193], v[232:233], 0, s[56:57]
	s_mov_b32 m0, s38
	s_nop 0
	global_load_lds_dwordx4 v[192:193], off
	v_lshl_add_u64 v[192:193], v[234:235], 0, s[56:57]
	s_add_i32 m0, s38, 0x2000
	s_nop 0
	global_load_lds_dwordx4 v[192:193], off
	v_lshl_add_u64 v[192:193], v[236:237], 0, s[56:57]
	s_mov_b32 m0, s79
	s_nop 0
	global_load_lds_dwordx4 v[192:193], off
	v_lshl_add_u64 v[192:193], v[238:239], 0, s[56:57]
	s_mov_b32 m0, s80
	s_nop 0
	global_load_lds_dwordx4 v[192:193], off
	s_waitcnt vmcnt(8)
	s_waitcnt lgkmcnt(0)
	s_setprio 1
	s_barrier
	v_mfma_f32_16x16x32_bf16 v[62:65], v[130:133], v[184:187], v[62:65]
	v_mfma_f32_16x16x32_bf16 v[58:61], v[138:141], v[184:187], v[58:61]
	v_mfma_f32_16x16x32_bf16 v[46:49], v[130:133], v[208:211], v[46:49]
	v_mfma_f32_16x16x32_bf16 v[42:45], v[138:141], v[208:211], v[42:45]
	v_mfma_f32_16x16x32_bf16 v[30:33], v[130:133], v[216:219], v[30:33]
	v_mfma_f32_16x16x32_bf16 v[26:29], v[138:141], v[216:219], v[26:29]
	v_mfma_f32_16x16x32_bf16 v[14:17], v[130:133], v[224:227], v[14:17]
	v_mfma_f32_16x16x32_bf16 v[10:13], v[138:141], v[224:227], v[10:13]
	v_mfma_f32_16x16x32_bf16 v[62:65], v[134:137], v[188:191], v[62:65]
	v_mfma_f32_16x16x32_bf16 v[58:61], v[142:145], v[188:191], v[58:61]
	v_mfma_f32_16x16x32_bf16 v[46:49], v[134:137], v[212:215], v[46:49]
	v_mfma_f32_16x16x32_bf16 v[42:45], v[142:145], v[212:215], v[42:45]
	v_mfma_f32_16x16x32_bf16 v[30:33], v[134:137], v[220:223], v[30:33]
	v_mfma_f32_16x16x32_bf16 v[26:29], v[142:145], v[220:223], v[26:29]
	v_mfma_f32_16x16x32_bf16 v[14:17], v[134:137], v[228:231], v[14:17]
	v_mfma_f32_16x16x32_bf16 v[10:13], v[142:145], v[228:231], v[10:13]
	v_mfma_f32_16x16x32_bf16 v[54:57], v[146:149], v[184:187], v[54:57]
	v_mfma_f32_16x16x32_bf16 v[50:53], v[176:179], v[184:187], v[50:53]
	v_mfma_f32_16x16x32_bf16 v[38:41], v[146:149], v[208:211], v[38:41]
	v_mfma_f32_16x16x32_bf16 v[34:37], v[176:179], v[208:211], v[34:37]
	v_mfma_f32_16x16x32_bf16 v[22:25], v[146:149], v[216:219], v[22:25]
	v_mfma_f32_16x16x32_bf16 v[18:21], v[176:179], v[216:219], v[18:21]
	v_mfma_f32_16x16x32_bf16 v[6:9], v[146:149], v[224:227], v[6:9]
	v_mfma_f32_16x16x32_bf16 v[2:5], v[176:179], v[224:227], v[2:5]
	v_mfma_f32_16x16x32_bf16 v[54:57], v[150:153], v[188:191], v[54:57]
	v_mfma_f32_16x16x32_bf16 v[50:53], v[180:183], v[188:191], v[50:53]
	v_mfma_f32_16x16x32_bf16 v[38:41], v[150:153], v[212:215], v[38:41]
	v_mfma_f32_16x16x32_bf16 v[34:37], v[180:183], v[212:215], v[34:37]
	v_mfma_f32_16x16x32_bf16 v[22:25], v[150:153], v[220:223], v[22:25]
	v_mfma_f32_16x16x32_bf16 v[18:21], v[180:183], v[220:223], v[18:21]
	v_mfma_f32_16x16x32_bf16 v[6:9], v[150:153], v[228:231], v[6:9]
	s_barrier
	v_mfma_f32_16x16x32_bf16 v[2:5], v[180:183], v[228:231], v[2:5]
	s_setprio 0
	s_add_u32 s68, s68, 0x100
	s_addc_u32 s69, s69, 0
	s_add_u32 s50, s50, 0x100
	s_addc_u32 s51, s51, 0
	s_cmp_ge_u32 s85, s78
	s_mov_b32 s70, s85
	s_cbranch_scc0 .LBB0_618
	s_and_b64 vcc, exec, s[22:23]
	s_cbranch_vccz .LBB0_621
	s_barrier
